# plus attention full-tile PV: V fragments read straight into MFMA operand registers (24 v_mov per tile removed)
# speedup vs baseline: 1.0032x; 1.0032x over previous
.LBB0_294:
	v_sub_f32_e32 v10, v65, v4
	v_exp_f32_e32 v15, v10
	v_sub_f32_e32 v10, v50, v4
	v_sub_f32_e32 v50, v71, v4
	v_sub_f32_e32 v6, v48, v4
	v_sub_f32_e32 v8, v64, v4
	v_sub_f32_e32 v48, v69, v4
	v_exp_f32_e32 v69, v50
	v_sub_f32_e32 v50, v56, v4
	v_exp_f32_e32 v6, v6
	v_exp_f32_e32 v14, v8
	v_sub_f32_e32 v9, v49, v4
	v_exp_f32_e32 v56, v50
	v_sub_f32_e32 v50, v72, v4
	v_exp_f32_e32 v9, v9
	v_sub_f32_e32 v11, v66, v4
	v_sub_f32_e32 v49, v70, v4
	v_exp_f32_e32 v70, v50
	v_sub_f32_e32 v50, v57, v4
	v_exp_f32_e32 v10, v10
	v_exp_f32_e32 v64, v11
	v_sub_f32_e32 v11, v51, v4
	v_sub_f32_e32 v12, v67, v4
	v_exp_f32_e32 v57, v50
	v_sub_f32_e32 v50, v73, v4
	v_exp_f32_e32 v11, v11
	v_exp_f32_e32 v65, v12
	v_sub_f32_e32 v12, v52, v4
	v_sub_f32_e32 v13, v68, v4
	v_exp_f32_e32 v71, v50
	v_sub_f32_e32 v50, v58, v4
	v_add_f32_e32 v7, 0, v6
	v_add_f32_e32 v8, 0, v14
	v_exp_f32_e32 v12, v12
	v_exp_f32_e32 v66, v13
	v_sub_f32_e32 v13, v53, v4
	v_exp_f32_e32 v58, v50
	v_sub_f32_e32 v50, v74, v4
	v_add_f32_e32 v7, v9, v7
	v_add_f32_e32 v8, v15, v8
	v_exp_f32_e32 v13, v13
	v_exp_f32_e32 v67, v48
	v_sub_f32_e32 v48, v54, v4
	v_exp_f32_e32 v72, v50
	v_sub_f32_e32 v50, v59, v4
	v_add_f32_e32 v7, v10, v7
	v_add_f32_e32 v8, v64, v8
	v_exp_f32_e32 v48, v48
	v_exp_f32_e32 v68, v49
	v_sub_f32_e32 v49, v55, v4
	v_exp_f32_e32 v73, v50
	v_sub_f32_e32 v50, v75, v4
	v_add_f32_e32 v7, v11, v7
	v_add_f32_e32 v8, v65, v8
	v_exp_f32_e32 v49, v49
	v_exp_f32_e32 v74, v50
	v_sub_f32_e32 v50, v60, v4
	v_add_f32_e32 v7, v12, v7
	v_add_f32_e32 v8, v66, v8
	v_exp_f32_e32 v60, v50
	v_sub_f32_e32 v50, v76, v4
	v_add_f32_e32 v7, v13, v7
	v_add_f32_e32 v8, v67, v8
	v_exp_f32_e32 v75, v50
	v_sub_f32_e32 v50, v61, v4
	v_add_f32_e32 v7, v48, v7
	v_add_f32_e32 v8, v68, v8
	v_exp_f32_e32 v61, v50
	v_sub_f32_e32 v50, v77, v4
	v_add_f32_e32 v7, v49, v7
	v_add_f32_e32 v8, v69, v8
	v_exp_f32_e32 v76, v50
	v_sub_f32_e32 v50, v62, v4
	v_add_f32_e32 v7, v56, v7
	v_add_f32_e32 v8, v70, v8
	v_exp_f32_e32 v62, v50
	v_sub_f32_e32 v50, v78, v4
	v_add_f32_e32 v7, v57, v7
	v_add_f32_e32 v8, v71, v8
	v_exp_f32_e32 v77, v50
	v_sub_f32_e32 v50, v63, v4
	v_add_f32_e32 v7, v58, v7
	v_add_f32_e32 v8, v72, v8
	v_exp_f32_e32 v63, v50
	v_sub_f32_e32 v50, v79, v4
	v_add_f32_e32 v7, v73, v7
	v_add_f32_e32 v8, v74, v8
	v_exp_f32_e32 v78, v50
	v_add_f32_e32 v7, v60, v7
	v_add_f32_e32 v8, v75, v8
	v_add_f32_e32 v7, v61, v7
	v_add_f32_e32 v8, v76, v8
	v_add_f32_e32 v7, v62, v7
	v_add_f32_e32 v8, v77, v8
	v_add_f32_e32 v7, v63, v7
	v_add_f32_e32 v8, v78, v8
	v_add_f32_e32 v59, v8, v7
	v_fmac_f32_e32 v59, v177, v0
	v_cvt_pkrtz_f16_f32 v7, v10, v11
	v_cvt_pkrtz_f16_f32 v8, v12, v13
	v_cvt_pkrtz_f16_f32 v6, v6, v9
	v_cvt_pkrtz_f16_f32 v9, v48, v49
	v_add_u32_e32 v0, v5, v184
	v_add_u32_e32 v196, v5, v182
	ds_read_b64 v[52:53], v0
	ds_read_b64 v[48:49], v0 offset:4096
	ds_read_b64 v[54:55], v196
	ds_read_b64 v[50:51], v196 offset:4096
	v_add_u32_e32 v0, v5, v2
	v_add_u32_e32 v196, v5, v1
	ds_read_b64 v[192:193], v0
	ds_read_b64 v[188:189], v0 offset:4096
	ds_read_b64 v[194:195], v196
	ds_read_b64 v[190:191], v196 offset:4096
	v_cvt_pkrtz_f16_f32 v10, v56, v57
	v_cvt_pkrtz_f16_f32 v11, v58, v73
	v_cvt_pkrtz_f16_f32 v12, v60, v61
	v_cvt_pkrtz_f16_f32 v13, v62, v63
	s_waitcnt lgkmcnt(4)
	v_mfma_f32_32x32x16_f16 v[32:47], v[48:51], v[6:9], v[32:47]
	v_mfma_f32_32x32x16_f16 v[16:31], v[52:55], v[6:9], v[16:31]
	v_add_u32_e32 v0, v5, v179
	v_add_u32_e32 v196, v5, v178
	ds_read_b64 v[52:53], v0
	ds_read_b64 v[48:49], v0 offset:4096
	ds_read_b64 v[54:55], v196 offset:8192
	ds_read_b64 v[50:51], v196 offset:12288
	v_cvt_pkrtz_f16_f32 v6, v14, v15
	v_cvt_pkrtz_f16_f32 v7, v64, v65
	v_cvt_pkrtz_f16_f32 v8, v66, v67
	v_cvt_pkrtz_f16_f32 v9, v68, v69
	s_waitcnt lgkmcnt(4)
	v_mfma_f32_32x32x16_f16 v[32:47], v[188:191], v[10:13], v[32:47]
	v_mfma_f32_32x32x16_f16 v[16:31], v[192:195], v[10:13], v[16:31]
	v_add_u32_e32 v0, v5, v181
	v_add_u32_e32 v196, v5, v180
	ds_read_b64 v[192:193], v0
	ds_read_b64 v[188:189], v0 offset:4096
	ds_read_b64 v[194:195], v196
	ds_read_b64 v[190:191], v196 offset:4096
	v_cvt_pkrtz_f16_f32 v13, v77, v78
	v_cvt_pkrtz_f16_f32 v10, v70, v71
	v_cvt_pkrtz_f16_f32 v11, v72, v74
	v_cvt_pkrtz_f16_f32 v12, v75, v76
	s_waitcnt lgkmcnt(4)
	v_mfma_f32_32x32x16_f16 v[32:47], v[48:51], v[6:9], v[32:47]
	v_mfma_f32_32x32x16_f16 v[16:31], v[52:55], v[6:9], v[16:31]
	s_waitcnt lgkmcnt(0)
	v_mfma_f32_32x32x16_f16 v[32:47], v[188:191], v[10:13], v[32:47]
	v_mfma_f32_32x32x16_f16 v[16:31], v[192:195], v[10:13], v[16:31]
